# grid-barrier closing s_barrier moved into the next GEMM prologue, after the weight-tile DMA issue
# baseline (speedup 1.0000x reference)
; __device__ __forceinline__ unsigned xb_ld(unsigned* p)              { return __hip_atomic_load(p, __ATOMIC_RELAXED, __HIP_MEMORY_SCOPE_AGENT); }
; #define XB_SPIN(cond, bar) do { unsigned _sp = 0; while (cond) { __builtin_amdgcn_s_sleep(1); \
;     if ((++_sp & 255u) == 0u) { if (xb_ld(&(bar)[XB_TMO])) break; if (_sp > XB_SPIN_CAP) { atomicAdd(&(bar)[XB_TMO], 1u); break; } } } } while (0)
; __device__ __forceinline__ void xcd_barrier(const XcdBarrier& b) {
;     ...
;         } else {
;             XB_SPIN(xb_ld(&bar[XB_XGEN(b.x)]) == gen, bar);
;             __builtin_amdgcn_fence(__ATOMIC_ACQUIRE, "agent");
;             asm volatile("s_waitcnt vmcnt(0)" ::: "memory");
;         }
;     }
;     __syncthreads();
.LBB0_202:
	s_or_b64 exec, exec, s[2:3]
	s_waitcnt lgkmcnt(0)
	s_nop 0

; #define PG8_WAIT_V(n) asm volatile("s_waitcnt vmcnt(" #n ")" ::: "memory")
; template <class Epi, bool ALIGN_EPI = PG8_ALIGN>
; __device__ __forceinline__ void gemm_phase(LAS unsigned char* lds, const Gemm g, const StaticOrder& S, const Epi& E) {
;     int tid = threadIdx.x; asm volatile("" : "+v"(tid));
;     const int wid = __builtin_amdgcn_readfirstlane(tid >> 6), lane = tid & 63, wr = wid >> 2, wc = wid & 3, fr = lane & 15, fq = lane >> 4;
;     int K = g.K; asm volatile("" : "+s"(K)); const int nt = K / BK, lda = g.lda;
;     unsigned voffA[2], voffB[2];
; #pragma unroll
;     for (int i = 0; i < 2; ++i) { int R, C; stage_rc(tid * 16 + i * 8192, R, C); const int Rb = Epi::PERM ? ((R & ~31) + perm32(R & 31)) : R;
;         voffA[i] = (unsigned)(R * lda + C) * 2u; voffB[i] = (unsigned)(Rb * K + C) * 2u; }
;     const size_t kstep = (size_t)(BK * 2);
;     const size_t hstepA = (size_t)HALF * lda * 2, hstepB = (size_t)HALF * K * 2;
;     const size_t tstepA = 2 * hstepA, tstepB = 2 * hstepB;
;     const unsigned ldsw = (unsigned)wid * 1024u;
;     const int aoff = lds_byte(wr * 64 + fr, fq * 8), boff = lds_byte(wc * 32 + fr, fq * 8);
;     ...
;     Unit cur, nxt; int ui = 0;
;     if (!S.next(0, cur)) return;
;     f32x4 acc[2][2][4][2];
; #pragma unroll
;     for (int a = 0; a < 2; ++a)
; #pragma unroll
;         for (int b = 0; b < 2; ++b)
; #pragma unroll
;             for (int m = 0; m < 4; ++m)
; #pragma unroll
;                 for (int n = 0; n < 2; ++n) acc[a][b][m][n] = (f32x4){0.f, 0.f, 0.f, 0.f};
;     bf16x8 At[4][2], B0[2][2], B1[2][2];
;     const char* cA = (const char*)g.A + (size_t)cur.pm * tstepA; const char* cB = (const char*)g.Bt + (size_t)cur.pn * tstepB;
;     PG8_STAGE(PG8_SB(0, 0), cB, voffB); PG8_STAGE(PG8_SB(0, 1), cB + hstepB, voffB); PG8_STAGE(PG8_SA(0, 0), cA, voffA); PG8_STAGE(PG8_SA(0, 1), cA + hstepA, voffA);
;     if (wr == 1) PG8_BAR;
;     PG8_WAIT_V(2); PG8_BAR;
; template <int PHM, int MIXM>
; __global__ void __launch_bounds__(512, 2) mega(Args Aval) {
;     ...
;         if ((PHM & 2) && IN(pb + 0)) {
;           for (int rep = 0; rep < ((PROBE_DUP & 2) ? 2 : 1); ++rep)
;             { pg8::Gemm g{XB, (const bf16_t*)(wl + WL_W1T), T, 2 * DFF, DM, DM}; pg8::StaticOrder S; S.init(T, 2 * DFF, G, bx);
;               pg8::EpiSwiGLU E{(bf16_t*)(ws + WS_ACT), nullptr, nullptr, 44}; pg8::gemm_phase(ldsl, g, S, E); }
.LBB0_206:
	s_andn2_b64 vcc, exec, s[2:3]
	s_cbranch_vccnz .LBB0_276
	v_readlane_b32 s4, v252, 11
	v_mov_b32_e32 v0, v238
	v_readlane_b32 s5, v252, 12
	s_movk_i32 s2, 0x800
	v_readfirstlane_b32 s12, v0
	s_andn2_b64 vcc, exec, s[4:5]
	s_cbranch_vccnz .LBB0_226
	v_lshlrev_b32_e32 v4, 4, v0
	v_add_u32_e32 v2, 0x2000, v4
	v_ashrrev_i32_e32 v1, 31, v2
	v_lshrrev_b32_e32 v1, 22, v1
	v_add_u32_e32 v1, v2, v1
	v_ashrrev_i32_e32 v1, 10, v1
	v_mul_i32_i24_e32 v3, 0x400, v1
	v_sub_u32_e32 v2, v2, v3
	v_lshrrev_b32_e32 v3, 4, v2
	v_bitop3_b32 v3, v3, v2, 32 bitop3:0x6c
	v_ashrrev_i32_e32 v2, 31, v3
	v_lshrrev_b32_e32 v2, 26, v2
	v_add_u32_e32 v5, v3, v2
	v_lshlrev_b32_e32 v6, 3, v1
	v_ashrrev_i32_e32 v2, 6, v5
	v_and_b32_e32 v6, -16, v6
	v_add_u32_e32 v6, v2, v6
	v_and_b32_e32 v7, 3, v2
	s_mov_b32 s8, 0x7fffffe0
	v_lshrrev_b32_e32 v8, 2, v6
	v_lshlrev_b32_e32 v9, 1, v6
	v_and_b32_e32 v5, 0xc0, v5
	v_and_or_b32 v7, v6, s8, v7
	v_and_b32_e32 v8, 4, v8
	v_and_b32_e32 v9, 24, v9
	v_sub_u32_e32 v3, v3, v5
	v_mov_b32_e32 v12, 1
	v_or3_b32 v7, v7, v8, v9
	v_lshlrev_b32_e32 v8, 5, v1
	v_ashrrev_i16_sdwa v3, v12, sext(v3) dst_sel:DWORD dst_unused:UNUSED_PAD src0_sel:DWORD src1_sel:BYTE_0
	v_and_b32_e32 v8, 32, v8
	v_bfe_i32 v3, v3, 0, 16
	v_mul_lo_u32 v7, v7, s2
	v_add_u32_e32 v5, v8, v3
	v_lshlrev_b32_e32 v6, 12, v6
	v_add_lshl_u32 v128, v7, v5, 1
	v_lshl_add_u32 v130, v5, 1, v6
	v_bfe_i32 v5, v0, 27, 1
	v_lshrrev_b32_e32 v5, 22, v5
	v_add_u32_e32 v5, v4, v5
	v_and_b32_e32 v5, 0xfffffc00, v5
	v_sub_u32_e32 v4, v4, v5
	v_lshrrev_b32_e32 v5, 4, v4
	v_bitop3_b32 v6, v5, v4, 32 bitop3:0x6c
	v_ashrrev_i32_e32 v5, 31, v0
	v_lshrrev_b32_e32 v5, 26, v5
	v_ashrrev_i32_e32 v4, 31, v6
	v_add_u32_e32 v5, v0, v5
	v_lshrrev_b32_e32 v4, 26, v4
	v_ashrrev_i32_e32 v5, 6, v5
	v_add_u32_e32 v7, v6, v4
	v_lshlrev_b32_e32 v8, 3, v5
	s_ashr_i32 s3, s2, 31
	v_ashrrev_i32_e32 v4, 6, v7
	v_and_b32_e32 v8, -16, v8
	v_readlane_b32 s16, v253, 52
	s_lshl_b64 s[6:7], s[2:3], 9
	v_add_u32_e32 v8, v4, v8
	v_and_b32_e32 v9, 3, v4
	v_readlane_b32 s17, v253, 53
	v_and_or_b32 v9, v8, s8, v9
	s_mul_i32 s8, s6, s17
	s_mul_hi_u32 s9, s6, s16
	v_lshrrev_b32_e32 v10, 2, v8
	v_lshlrev_b32_e32 v11, 1, v8
	v_and_b32_e32 v7, 0xc0, v7
	s_add_i32 s10, s9, s8
	s_lshr_b64 s[8:9], s[2:3], 23
	s_ashr_i32 s13, s12, 6
	v_and_b32_e32 v10, 4, v10
	v_and_b32_e32 v11, 24, v11
	v_sub_u32_e32 v6, v6, v7
	s_mul_i32 s8, s8, s16
	s_ashr_i32 s14, s12, 8
	s_lshl_b64 s[4:5], s[2:3], 8
	s_lshl_b32 s18, s13, 10
	v_or3_b32 v9, v9, v10, v11
	v_lshlrev_b32_e32 v10, 5, v5
	v_ashrrev_i16_sdwa v6, v12, sext(v6) dst_sel:DWORD dst_unused:UNUSED_PAD src0_sel:DWORD src1_sel:BYTE_0
	s_add_i32 s10, s10, s8
	s_mul_i32 s8, s6, s16
	v_readlane_b32 s9, v255, 17
	v_and_b32_e32 v10, 32, v10
	v_bfe_i32 v6, v6, 0, 16
	s_add_u32 s24, s9, s8
	v_readlane_b32 s8, v255, 18
	v_mul_lo_u32 v9, v9, s2
	v_add_u32_e32 v7, v10, v6
	s_addc_u32 s25, s8, s10
	s_add_i32 s29, s18, 16
	v_add_lshl_u32 v176, v9, v7, 1
	s_add_i32 m0, s29, 0x10000
	v_lshlrev_b32_e32 v8, 12, v8
	global_load_lds_dwordx4 v176, s[24:25]
	s_add_i32 m0, s29, 0x12000
	s_add_u32 s10, s24, s4
	global_load_lds_dwordx4 v128, s[24:25]
	s_addc_u32 s11, s25, s5
	s_add_i32 m0, s29, 0x14000
	v_readlane_b32 s8, v253, 56
	global_load_lds_dwordx4 v176, s[10:11]
	s_add_i32 m0, s29, 0x16000
	v_lshl_add_u32 v132, v7, 1, v8
	global_load_lds_dwordx4 v128, s[10:11]
	s_mov_b32 m0, s29
	v_readlane_b32 s9, v253, 57
	s_add_i32 s30, s29, 0x2000
	s_add_i32 s31, s29, 0x4000
	s_add_i32 s42, s29, 0x6000
	s_cmp_eq_u32 s14, 1
	s_nop 0
	s_barrier
	global_load_lds_dwordx4 v132, s[8:9]
	s_mov_b32 m0, s30
	s_nop 0
	global_load_lds_dwordx4 v130, s[8:9]
	v_readlane_b32 s8, v253, 58
	s_mov_b32 m0, s31
	v_readlane_b32 s9, v253, 59
	s_nop 4
	global_load_lds_dwordx4 v132, s[8:9]
	s_mov_b32 m0, s42
	s_nop 0
	global_load_lds_dwordx4 v130, s[8:9]
	s_cselect_b64 s[8:9], -1, 0
	s_cmp_lg_u32 s14, 1
	s_cbranch_scc1 .LBB0_210
	s_barrier

; #define PG8_WAIT_V(n) asm volatile("s_waitcnt vmcnt(" #n ")" ::: "memory")
; template <class Epi, bool ALIGN_EPI = PG8_ALIGN>
; __device__ __forceinline__ void gemm_phase(LAS unsigned char* lds, const Gemm g, const StaticOrder& S, const Epi& E) {
;     int tid = threadIdx.x; asm volatile("" : "+v"(tid));
;     const int wid = __builtin_amdgcn_readfirstlane(tid >> 6), lane = tid & 63, wr = wid >> 2, wc = wid & 3, fr = lane & 15, fq = lane >> 4;
;     int K = g.K; asm volatile("" : "+s"(K)); const int nt = K / BK, lda = g.lda;
;     unsigned voffA[2], voffB[2];
; #pragma unroll
;     for (int i = 0; i < 2; ++i) { int R, C; stage_rc(tid * 16 + i * 8192, R, C); const int Rb = Epi::PERM ? ((R & ~31) + perm32(R & 31)) : R;
;         voffA[i] = (unsigned)(R * lda + C) * 2u; voffB[i] = (unsigned)(Rb * K + C) * 2u; }
;     const size_t kstep = (size_t)(BK * 2);
;     const size_t hstepA = (size_t)HALF * lda * 2, hstepB = (size_t)HALF * K * 2;
;     const size_t tstepA = 2 * hstepA, tstepB = 2 * hstepB;
;     const unsigned ldsw = (unsigned)wid * 1024u;
;     const int aoff = lds_byte(wr * 64 + fr, fq * 8), boff = lds_byte(wc * 32 + fr, fq * 8);
;     ...
;     Unit cur, nxt; int ui = 0;
;     if (!S.next(0, cur)) return;
;     f32x4 acc[2][2][4][2];
; #pragma unroll
;     for (int a = 0; a < 2; ++a)
; #pragma unroll
;         for (int b = 0; b < 2; ++b)
; #pragma unroll
;             for (int m = 0; m < 4; ++m)
; #pragma unroll
;                 for (int n = 0; n < 2; ++n) acc[a][b][m][n] = (f32x4){0.f, 0.f, 0.f, 0.f};
;     bf16x8 At[4][2], B0[2][2], B1[2][2];
;     const char* cA = (const char*)g.A + (size_t)cur.pm * tstepA; const char* cB = (const char*)g.Bt + (size_t)cur.pn * tstepB;
;     PG8_STAGE(PG8_SB(0, 0), cB, voffB); PG8_STAGE(PG8_SB(0, 1), cB + hstepB, voffB); PG8_STAGE(PG8_SA(0, 0), cA, voffA); PG8_STAGE(PG8_SA(0, 1), cA + hstepA, voffA);
;     if (wr == 1) PG8_BAR;
;     PG8_WAIT_V(2); PG8_BAR;
; template <int PHM, int MIXM>
; __global__ void __launch_bounds__(512, 2) mega(Args Aval) {
;     ...
;         for (int rp = 0; rp < ((PROBE_DUP & 256) ? 2 : 1); ++rp) if ((PHM & 4) && IN(pb + 1)) { pg8::Gemm g{(const bf16_t*)(ws + WS_ACT), (const bf16_t*)(wl + WL_W1D), T, DM, DFF, DFF}; pg8::StaticOrder S; S.init(T, DM, G, bx);
;             pg8::EpiStore E{(bf16_t*)(ws + WS_MIX), DM, nullptr, 0, 0.5f}; pg8::gemm_phase(ldsl, g, S, E); }
.LBB0_276:
	v_readlane_b32 s2, v254, 61
	v_writelane_b32 v255, s52, 19
	v_readlane_b32 s3, v254, 62
	s_xor_b64 s[2:3], s[2:3], -1
	v_writelane_b32 v255, s53, 20
	v_writelane_b32 v255, s2, 21
	v_readlane_b32 s4, v252, 0
	v_readlane_b32 s5, v252, 1
	v_writelane_b32 v255, s3, 22
	v_readlane_b32 s2, v252, 2
	v_readlane_b32 s3, v252, 3
	s_cmp_le_i32 s4, s18
	s_cselect_b64 s[2:3], -1, 0
	s_cmp_lt_i32 s18, s5
	s_cselect_b64 s[4:5], -1, 0
	s_and_b64 s[4:5], s[2:3], s[4:5]
	v_readlane_b32 s2, v253, 23
	v_readlane_b32 s3, v253, 24
	s_andn2_b64 vcc, exec, s[4:5]
	s_nop 0
	v_cndmask_b32_e64 v0, 0, 1, s[2:3]
	v_cmp_ne_u32_e64 s[2:3], 1, v0
	s_nop 1
	v_writelane_b32 v255, s2, 23
	s_nop 1
	v_writelane_b32 v255, s3, 24
	s_cbranch_vccnz .LBB0_303
	v_readlane_b32 s6, v255, 23
	v_mov_b32_e32 v8, v238
	v_readlane_b32 s7, v255, 24
	s_movk_i32 s2, 0x1600
	v_readfirstlane_b32 s14, v8
	s_and_b64 vcc, exec, s[6:7]
	s_cbranch_vccnz .LBB0_303
	v_lshlrev_b32_e32 v0, 4, v8
	v_add_u32_e32 v1, 0x2000, v0
	v_ashrrev_i32_e32 v2, 31, v1
	v_lshrrev_b32_e32 v2, 22, v2
	v_add_u32_e32 v2, v1, v2
	v_ashrrev_i32_e32 v9, 10, v2
	v_mul_i32_i24_e32 v2, 0x400, v9
	v_sub_u32_e32 v1, v1, v2
	v_lshrrev_b32_e32 v2, 4, v1
	v_bitop3_b32 v1, v2, v1, 32 bitop3:0x6c
	v_ashrrev_i32_e32 v2, 31, v1
	v_lshrrev_b32_e32 v2, 26, v2
	s_ashr_i32 s12, s14, 6
	s_ashr_i32 s3, s2, 31
	v_add_u32_e32 v2, v1, v2
	v_lshlrev_b32_e32 v3, 3, v9
	s_ashr_i32 s13, s14, 8
	s_lshl_b64 s[6:7], s[2:3], 8
	s_lshl_b64 s[8:9], s[2:3], 9
	s_lshl_b32 s18, s12, 10
	v_readlane_b32 s10, v255, 17
	v_ashrrev_i32_e32 v10, 6, v2
	v_and_b32_e32 v3, -16, v3
	s_add_u32 s29, s10, 0x2c00000
	v_readlane_b32 s10, v255, 18
	v_add_u32_e32 v3, v10, v3
	s_addc_u32 s30, s10, 0
	v_and_b32_e32 v4, 3, v10
	s_mov_b32 s10, 0x7fffffe0
	v_lshrrev_b32_e32 v5, 2, v3
	v_lshlrev_b32_e32 v6, 1, v3
	v_and_or_b32 v4, v3, s10, v4
	v_and_b32_e32 v5, 4, v5
	v_and_b32_e32 v6, 24, v6
	v_and_b32_e32 v2, 0xc0, v2
	v_or3_b32 v4, v4, v5, v6
	v_sub_u32_e32 v1, v1, v2
	v_mov_b32_e32 v6, 1
	v_lshlrev_b32_e32 v5, 5, v9
	v_ashrrev_i16_sdwa v1, v6, sext(v1) dst_sel:DWORD dst_unused:UNUSED_PAD src0_sel:DWORD src1_sel:BYTE_0
	v_and_b32_e32 v11, 32, v5
	v_bfe_i32 v12, v1, 0, 16
	s_movk_i32 s11, 0x1600
	v_mul_lo_u32 v4, v4, s2
	v_add_u32_e32 v1, v11, v12
	v_mul_lo_u32 v2, v3, s11
	v_add_lshl_u32 v128, v4, v1, 1
	v_add_lshl_u32 v130, v1, v2, 1
	v_bfe_i32 v1, v8, 27, 1
	v_lshrrev_b32_e32 v1, 22, v1
	v_add_u32_e32 v1, v0, v1
	v_and_b32_e32 v1, 0xfffffc00, v1
	v_sub_u32_e32 v0, v0, v1
	v_lshrrev_b32_e32 v1, 4, v0
	v_ashrrev_i32_e32 v2, 31, v8
	v_bitop3_b32 v0, v1, v0, 32 bitop3:0x6c
	v_lshrrev_b32_e32 v2, 26, v2
	v_ashrrev_i32_e32 v1, 31, v0
	v_add_u32_e32 v2, v8, v2
	v_lshrrev_b32_e32 v1, 26, v1
	v_ashrrev_i32_e32 v14, 6, v2
	v_add_u32_e32 v1, v0, v1
	v_lshlrev_b32_e32 v2, 3, v14
	v_ashrrev_i32_e32 v13, 6, v1
	v_and_b32_e32 v2, -16, v2
	v_readlane_b32 s16, v253, 61
	v_add_u32_e32 v2, v13, v2
	v_and_b32_e32 v3, 3, v13
	v_and_b32_e32 v1, 0xc0, v1
	v_readlane_b32 s17, v253, 62
	v_and_or_b32 v3, v2, s10, v3
	v_sub_u32_e32 v0, v0, v1
	v_mul_lo_u32 v1, v2, s11
	s_mul_i32 s10, s8, s17
	s_mul_hi_u32 s11, s8, s16
	v_lshrrev_b32_e32 v4, 2, v2
	v_lshlrev_b32_e32 v5, 1, v2
	s_add_i32 s15, s11, s10
	s_lshr_b64 s[10:11], s[2:3], 23
	v_and_b32_e32 v4, 4, v4
	v_and_b32_e32 v5, 24, v5
	s_mul_i32 s10, s10, s16
	v_or3_b32 v3, v3, v4, v5
	v_lshlrev_b32_e32 v4, 5, v14
	v_ashrrev_i16_sdwa v0, v6, sext(v0) dst_sel:DWORD dst_unused:UNUSED_PAD src0_sel:DWORD src1_sel:BYTE_0
	s_add_i32 s15, s15, s10
	s_mul_i32 s10, s8, s16
	v_and_b32_e32 v15, 32, v4
	v_bfe_i32 v16, v0, 0, 16
	s_add_u32 s36, s29, s10
	v_mul_lo_u32 v3, v3, s2
	v_add_u32_e32 v0, v15, v16
	s_addc_u32 s37, s30, s15
	s_add_i32 s31, s18, 16
	v_add_lshl_u32 v176, v3, v0, 1
	s_add_i32 m0, s31, 0x10000
	v_mov_b32_e32 v129, v177
	global_load_lds_dwordx4 v176, s[36:37]
	s_add_i32 m0, s31, 0x12000
	s_add_u32 s10, s36, s6
	global_load_lds_dwordx4 v128, s[36:37]
	s_addc_u32 s11, s37, s7
	s_add_i32 m0, s31, 0x14000
	v_lshl_add_u64 v[4:5], s[10:11], 0, v[176:177]
	global_load_lds_dwordx4 v176, s[10:11]
	s_add_i32 m0, s31, 0x16000
	v_lshl_add_u64 v[6:7], s[10:11], 0, v[128:129]
	global_load_lds_dwordx4 v128, s[10:11]
	v_readlane_b32 s10, v253, 63
	v_add_lshl_u32 v132, v0, v1, 1
	s_mov_b32 m0, s31
	v_readlane_b32 s11, v254, 0
	s_add_i32 s40, s31, 0x2000
	s_add_i32 s41, s31, 0x4000
	s_add_i32 s44, s31, 0x6000
	s_cmp_eq_u32 s13, 1
	v_lshl_add_u64 v[0:1], s[36:37], 0, v[176:177]
	s_barrier
	global_load_lds_dwordx4 v132, s[10:11]
	s_mov_b32 m0, s40
	v_lshl_add_u64 v[2:3], s[36:37], 0, v[128:129]
	global_load_lds_dwordx4 v130, s[10:11]
	v_readlane_b32 s10, v254, 1
	s_mov_b32 m0, s41
	v_readlane_b32 s11, v254, 2
	s_nop 4
	global_load_lds_dwordx4 v132, s[10:11]
	s_mov_b32 m0, s44
	s_nop 0
	global_load_lds_dwordx4 v130, s[10:11]
	s_cselect_b64 s[10:11], -1, 0
	s_cmp_lg_u32 s13, 1
	s_cbranch_scc1 .LBB0_280
	s_barrier

; #define PG8_WAIT_V(n) asm volatile("s_waitcnt vmcnt(" #n ")" ::: "memory")
; #define PG8_BAR __builtin_amdgcn_s_barrier()
; template <class Epi, bool ALIGN_EPI = PG8_ALIGN>
; __device__ __forceinline__ void gemm_phase(LAS unsigned char* lds, const Gemm g, const StaticOrder& S, const Epi& E) {
;     int tid = threadIdx.x; asm volatile("" : "+v"(tid));
;     const int wid = __builtin_amdgcn_readfirstlane(tid >> 6), lane = tid & 63, wr = wid >> 2, wc = wid & 3, fr = lane & 15, fq = lane >> 4;
;     int K = g.K; asm volatile("" : "+s"(K)); const int nt = K / BK, lda = g.lda;
;     unsigned voffA[2], voffB[2];
; #pragma unroll
;     for (int i = 0; i < 2; ++i) { int R, C; stage_rc(tid * 16 + i * 8192, R, C); const int Rb = Epi::PERM ? ((R & ~31) + perm32(R & 31)) : R;
;         voffA[i] = (unsigned)(R * lda + C) * 2u; voffB[i] = (unsigned)(Rb * K + C) * 2u; }
;     const size_t kstep = (size_t)(BK * 2);
;     const size_t hstepA = (size_t)HALF * lda * 2, hstepB = (size_t)HALF * K * 2;
;     const size_t tstepA = 2 * hstepA, tstepB = 2 * hstepB;
;     const unsigned ldsw = (unsigned)wid * 1024u;
;     const int aoff = lds_byte(wr * 64 + fr, fq * 8), boff = lds_byte(wc * 32 + fr, fq * 8);
;     ...
;     Unit cur, nxt; int ui = 0;
;     if (!S.next(0, cur)) return;
;     f32x4 acc[2][2][4][2];
; #pragma unroll
;     for (int a = 0; a < 2; ++a)
; #pragma unroll
;         for (int b = 0; b < 2; ++b)
; #pragma unroll
;             for (int m = 0; m < 4; ++m)
; #pragma unroll
;                 for (int n = 0; n < 2; ++n) acc[a][b][m][n] = (f32x4){0.f, 0.f, 0.f, 0.f};
;     bf16x8 At[4][2], B0[2][2], B1[2][2];
;     const char* cA = (const char*)g.A + (size_t)cur.pm * tstepA; const char* cB = (const char*)g.Bt + (size_t)cur.pn * tstepB;
;     PG8_STAGE(PG8_SB(0, 0), cB, voffB); PG8_STAGE(PG8_SB(0, 1), cB + hstepB, voffB); PG8_STAGE(PG8_SA(0, 0), cA, voffA); PG8_STAGE(PG8_SA(0, 1), cA + hstepA, voffA);
;     if (wr == 1) PG8_BAR;
;     PG8_WAIT_V(2); PG8_BAR;
; template <int PHM, int MIXM>
; __global__ void __launch_bounds__(512, 2) mega(Args Aval) {
;     ...
;         for (int rp = 0; rp < ((PROBE_DUP & 512) ? 2 : 1); ++rp) if ((PHM & 16) && IN(pb + 3)) { pg8::Gemm g{XB, (const bf16_t*)(wl + WL_WIN), T, INWP, DM, DM}; pg8::StaticOrder S; S.init(T, INWP, G, bx);
;             pg8::EpiStore E{(bf16_t*)(ws + WS_PROJ), INWP, nullptr, 0, 1.f}; pg8::gemm_phase(ldsl, g, S, E); }
.LBB0_445:
	s_andn2_b64 vcc, exec, s[2:3]
	s_cbranch_vccnz .LBB0_538
	v_readlane_b32 s4, v253, 25
	v_mov_b32_e32 v0, v238
	v_readlane_b32 s5, v253, 26
	s_movk_i32 s2, 0x800
	v_readfirstlane_b32 s14, v0
	s_andn2_b64 vcc, exec, s[4:5]
	s_cbranch_vccnz .LBB0_465
	v_lshlrev_b32_e32 v4, 4, v0
	v_add_u32_e32 v2, 0x2000, v4
	v_ashrrev_i32_e32 v1, 31, v2
	v_lshrrev_b32_e32 v1, 22, v1
	v_add_u32_e32 v1, v2, v1
	v_ashrrev_i32_e32 v1, 10, v1
	v_mul_i32_i24_e32 v3, 0x400, v1
	v_sub_u32_e32 v2, v2, v3
	v_lshrrev_b32_e32 v3, 4, v2
	v_bitop3_b32 v3, v3, v2, 32 bitop3:0x6c
	v_ashrrev_i32_e32 v2, 31, v3
	v_lshrrev_b32_e32 v2, 26, v2
	s_ashr_i32 s12, s14, 6
	s_ashr_i32 s3, s2, 31
	v_add_u32_e32 v5, v3, v2
	v_lshlrev_b32_e32 v6, 3, v1
	s_ashr_i32 s13, s14, 8
	s_lshl_b64 s[6:7], s[2:3], 8
	s_lshl_b64 s[8:9], s[2:3], 9
	s_lshl_b32 s18, s12, 10
	v_readlane_b32 s4, v255, 17
	v_ashrrev_i32_e32 v2, 6, v5
	v_and_b32_e32 v6, -16, v6
	s_add_u32 s26, s4, 0x4200000
	v_readlane_b32 s4, v255, 18
	v_add_u32_e32 v6, v2, v6
	s_addc_u32 s27, s4, 0
	v_and_b32_e32 v7, 3, v2
	s_mov_b32 s4, 0x7fffffe0
	v_lshrrev_b32_e32 v8, 2, v6
	v_lshlrev_b32_e32 v9, 1, v6
	v_and_b32_e32 v5, 0xc0, v5
	v_and_or_b32 v7, v6, s4, v7
	v_and_b32_e32 v8, 4, v8
	v_and_b32_e32 v9, 24, v9
	v_sub_u32_e32 v3, v3, v5
	v_mov_b32_e32 v12, 1
	v_or3_b32 v7, v7, v8, v9
	v_lshlrev_b32_e32 v8, 5, v1
	v_ashrrev_i16_sdwa v3, v12, sext(v3) dst_sel:DWORD dst_unused:UNUSED_PAD src0_sel:DWORD src1_sel:BYTE_0
	v_and_b32_e32 v8, 32, v8
	v_bfe_i32 v3, v3, 0, 16
	v_mul_lo_u32 v7, v7, s2
	v_add_u32_e32 v5, v8, v3
	v_lshlrev_b32_e32 v6, 12, v6
	v_add_lshl_u32 v128, v7, v5, 1
	v_lshl_add_u32 v130, v5, 1, v6
	v_bfe_i32 v5, v0, 27, 1
	v_lshrrev_b32_e32 v5, 22, v5
	v_add_u32_e32 v5, v4, v5
	v_and_b32_e32 v5, 0xfffffc00, v5
	v_sub_u32_e32 v4, v4, v5
	v_lshrrev_b32_e32 v5, 4, v4
	v_bitop3_b32 v6, v5, v4, 32 bitop3:0x6c
	v_ashrrev_i32_e32 v5, 31, v0
	v_lshrrev_b32_e32 v5, 26, v5
	v_ashrrev_i32_e32 v4, 31, v6
	v_add_u32_e32 v5, v0, v5
	v_lshrrev_b32_e32 v4, 26, v4
	v_ashrrev_i32_e32 v5, 6, v5
	v_add_u32_e32 v7, v6, v4
	v_lshlrev_b32_e32 v8, 3, v5
	v_ashrrev_i32_e32 v4, 6, v7
	v_and_b32_e32 v8, -16, v8
	v_readlane_b32 s16, v254, 4
	v_add_u32_e32 v8, v4, v8
	v_and_b32_e32 v9, 3, v4
	v_readlane_b32 s17, v254, 5
	v_and_or_b32 v9, v8, s4, v9
	s_mul_i32 s4, s8, s17
	s_mul_hi_u32 s5, s8, s16
	v_lshrrev_b32_e32 v10, 2, v8
	v_lshlrev_b32_e32 v11, 1, v8
	v_and_b32_e32 v7, 0xc0, v7
	s_add_i32 s10, s5, s4
	s_lshr_b64 s[4:5], s[2:3], 23
	v_and_b32_e32 v10, 4, v10
	v_and_b32_e32 v11, 24, v11
	v_sub_u32_e32 v6, v6, v7
	s_mul_i32 s4, s4, s16
	v_or3_b32 v9, v9, v10, v11
	v_lshlrev_b32_e32 v10, 5, v5
	v_ashrrev_i16_sdwa v6, v12, sext(v6) dst_sel:DWORD dst_unused:UNUSED_PAD src0_sel:DWORD src1_sel:BYTE_0
	s_add_i32 s10, s10, s4
	s_mul_i32 s4, s8, s16
	v_and_b32_e32 v10, 32, v10
	v_bfe_i32 v6, v6, 0, 16
	s_add_u32 s38, s26, s4
	v_mul_lo_u32 v9, v9, s2
	v_add_u32_e32 v7, v10, v6
	s_addc_u32 s39, s27, s10
	s_add_i32 s29, s18, 16
	v_add_lshl_u32 v176, v9, v7, 1
	s_add_i32 m0, s29, 0x10000
	v_lshlrev_b32_e32 v8, 12, v8
	global_load_lds_dwordx4 v176, s[38:39]
	s_add_i32 m0, s29, 0x12000
	s_add_u32 s4, s38, s6
	global_load_lds_dwordx4 v128, s[38:39]
	s_addc_u32 s5, s39, s7
	s_add_i32 m0, s29, 0x14000
	v_readlane_b32 s10, v254, 8
	global_load_lds_dwordx4 v176, s[4:5]
	s_add_i32 m0, s29, 0x16000
	v_lshl_add_u32 v132, v7, 1, v8
	global_load_lds_dwordx4 v128, s[4:5]
	s_mov_b32 m0, s29
	v_readlane_b32 s11, v254, 9
	s_add_i32 s30, s29, 0x2000
	s_add_i32 s31, s29, 0x4000
	s_add_i32 s42, s29, 0x6000
	s_cmp_eq_u32 s13, 1
	s_nop 0
	s_barrier
	global_load_lds_dwordx4 v132, s[10:11]
	s_mov_b32 m0, s30
	s_nop 0
	global_load_lds_dwordx4 v130, s[10:11]
	v_readlane_b32 s10, v254, 10
	s_mov_b32 m0, s31
	v_readlane_b32 s11, v254, 11
	s_nop 4
	global_load_lds_dwordx4 v132, s[10:11]
	s_mov_b32 m0, s42
	s_nop 0
	global_load_lds_dwordx4 v130, s[10:11]
	s_cselect_b64 s[10:11], -1, 0
	s_cmp_lg_u32 s13, 1
	s_cbranch_scc1 .LBB0_449
	s_barrier

; template <class Epi, bool ALIGN_EPI = PG8_ALIGN>
; __device__ __forceinline__ void gemm_phase(LAS unsigned char* lds, const Gemm g, const StaticOrder& S, const Epi& E) {
;     int tid = threadIdx.x; asm volatile("" : "+v"(tid));
;     const int wid = __builtin_amdgcn_readfirstlane(tid >> 6), lane = tid & 63, wr = wid >> 2, wc = wid & 3, fr = lane & 15, fq = lane >> 4;
;     int K = g.K; asm volatile("" : "+s"(K)); const int nt = K / BK, lda = g.lda;
;     unsigned voffA[2], voffB[2];
; #pragma unroll
;     for (int i = 0; i < 2; ++i) { int R, C; stage_rc(tid * 16 + i * 8192, R, C); const int Rb = Epi::PERM ? ((R & ~31) + perm32(R & 31)) : R;
;         voffA[i] = (unsigned)(R * lda + C) * 2u; voffB[i] = (unsigned)(Rb * K + C) * 2u; }
;     const size_t kstep = (size_t)(BK * 2);
;     const size_t hstepA = (size_t)HALF * lda * 2, hstepB = (size_t)HALF * K * 2;
;     const size_t tstepA = 2 * hstepA, tstepB = 2 * hstepB;
;     const unsigned ldsw = (unsigned)wid * 1024u;
;     const int aoff = lds_byte(wr * 64 + fr, fq * 8), boff = lds_byte(wc * 32 + fr, fq * 8);
;     ...
;     Unit cur, nxt; int ui = 0;
;     if (!S.next(0, cur)) return;
;     f32x4 acc[2][2][4][2];
; #pragma unroll
;     for (int a = 0; a < 2; ++a)
; #pragma unroll
;         for (int b = 0; b < 2; ++b)
; #pragma unroll
;             for (int m = 0; m < 4; ++m)
; #pragma unroll
;                 for (int n = 0; n < 2; ++n) acc[a][b][m][n] = (f32x4){0.f, 0.f, 0.f, 0.f};
;     bf16x8 At[4][2], B0[2][2], B1[2][2];
;     const char* cA = (const char*)g.A + (size_t)cur.pm * tstepA; const char* cB = (const char*)g.Bt + (size_t)cur.pn * tstepB;
;     PG8_STAGE(PG8_SB(0, 0), cB, voffB); PG8_STAGE(PG8_SB(0, 1), cB + hstepB, voffB); PG8_STAGE(PG8_SA(0, 0), cA, voffA); PG8_STAGE(PG8_SA(0, 1), cA + hstepA, voffA);
;     if (wr == 1) PG8_BAR;
;     PG8_WAIT_V(2); PG8_BAR;
;     PG8_STAGE(PG8_SB(1, 0), cB + kstep, voffB); PG8_STAGE(PG8_SA(1, 0), cA + kstep, voffA); PG8_STAGE(PG8_SB(1, 1), cB + hstepB + kstep, voffB);
; template <int PHM, int MIXM>
; __global__ void __launch_bounds__(512, 2) mega(Args Aval) {
;     ...
;             { pg8::Gemm g{(const bf16_t*)(ws + WS_PROJ) + C_CKV, (const bf16_t*)(wl + WL_WUKV), T, 1024, 256, INWP}; pg8::StaticOrder S; S.init(T, 1024, G, bx);
;               pg8::EpiStore E{(bf16_t*)(ws + WS_KVM), 1024, (const float*)(ws + WS_RSTD) + 1, 2, 1.f}; pg8::gemm_phase(ldsl, g, S, E); }
.LBB0_623:
	s_andn2_b64 vcc, exec, s[2:3]
	s_cbranch_vccnz .LBB0_725
	v_readlane_b32 s6, v253, 43
	v_mov_b32_e32 v8, v238
	v_readlane_b32 s7, v253, 44
	s_movk_i32 s2, 0x100
	v_readfirstlane_b32 s14, v8
	s_andn2_b64 vcc, exec, s[6:7]
	s_cbranch_vccnz .LBB0_649
	v_lshlrev_b32_e32 v0, 4, v8
	v_add_u32_e32 v1, 0x2000, v0
	v_ashrrev_i32_e32 v2, 31, v1
	v_lshrrev_b32_e32 v2, 22, v2
	v_add_u32_e32 v2, v1, v2
	v_ashrrev_i32_e32 v9, 10, v2
	v_mul_i32_i24_e32 v2, 0x400, v9
	v_sub_u32_e32 v1, v1, v2
	v_lshrrev_b32_e32 v2, 4, v1
	v_bitop3_b32 v1, v2, v1, 32 bitop3:0x6c
	v_ashrrev_i32_e32 v2, 31, v1
	v_lshrrev_b32_e32 v2, 26, v2
	v_add_u32_e32 v2, v1, v2
	v_lshlrev_b32_e32 v3, 3, v9
	v_ashrrev_i32_e32 v10, 6, v2
	v_and_b32_e32 v3, -16, v3
	v_add_u32_e32 v3, v10, v3
	v_and_b32_e32 v4, 3, v10
	s_mov_b32 s10, 0x7fffffe0
	v_lshrrev_b32_e32 v5, 2, v3
	v_lshlrev_b32_e32 v6, 1, v3
	v_and_or_b32 v4, v3, s10, v4
	v_and_b32_e32 v5, 4, v5
	v_and_b32_e32 v6, 24, v6
	v_and_b32_e32 v2, 0xc0, v2
	v_or3_b32 v4, v4, v5, v6
	v_sub_u32_e32 v1, v1, v2
	v_mov_b32_e32 v6, 1
	v_lshlrev_b32_e32 v5, 5, v9
	v_ashrrev_i16_sdwa v1, v6, sext(v1) dst_sel:DWORD dst_unused:UNUSED_PAD src0_sel:DWORD src1_sel:BYTE_0
	v_and_b32_e32 v11, 32, v5
	v_bfe_i32 v12, v1, 0, 16
	s_movk_i32 s11, 0x1100
	v_mul_lo_u32 v4, v4, s2
	v_add_u32_e32 v1, v11, v12
	v_mul_lo_u32 v2, v3, s11
	v_add_lshl_u32 v128, v4, v1, 1
	v_add_lshl_u32 v130, v1, v2, 1
	v_bfe_i32 v1, v8, 27, 1
	v_lshrrev_b32_e32 v1, 22, v1
	v_add_u32_e32 v1, v0, v1
	v_and_b32_e32 v1, 0xfffffc00, v1
	v_sub_u32_e32 v0, v0, v1
	v_lshrrev_b32_e32 v1, 4, v0
	v_ashrrev_i32_e32 v2, 31, v8
	v_bitop3_b32 v0, v1, v0, 32 bitop3:0x6c
	v_lshrrev_b32_e32 v2, 26, v2
	v_ashrrev_i32_e32 v1, 31, v0
	v_add_u32_e32 v2, v8, v2
	v_readlane_b32 s3, v255, 17
	v_lshrrev_b32_e32 v1, 26, v1
	v_ashrrev_i32_e32 v14, 6, v2
	s_add_u32 s18, s3, 0xa5c0000
	v_readlane_b32 s3, v255, 18
	v_add_u32_e32 v1, v0, v1
	v_lshlrev_b32_e32 v2, 3, v14
	s_addc_u32 s29, s3, 0
	s_ashr_i32 s3, s2, 31
	v_ashrrev_i32_e32 v13, 6, v1
	v_and_b32_e32 v2, -16, v2
	v_readlane_b32 s16, v254, 16
	s_lshl_b64 s[8:9], s[2:3], 9
	v_add_u32_e32 v2, v13, v2
	v_and_b32_e32 v3, 3, v13
	v_and_b32_e32 v1, 0xc0, v1
	v_readlane_b32 s17, v254, 17
	v_and_or_b32 v3, v2, s10, v3
	v_sub_u32_e32 v0, v0, v1
	v_mul_lo_u32 v1, v2, s11
	s_mul_i32 s10, s8, s17
	s_mul_hi_u32 s11, s8, s16
	v_lshrrev_b32_e32 v4, 2, v2
	v_lshlrev_b32_e32 v5, 1, v2
	s_add_i32 s15, s11, s10
	s_lshr_b64 s[10:11], s[2:3], 23
	s_ashr_i32 s12, s14, 6
	v_and_b32_e32 v4, 4, v4
	v_and_b32_e32 v5, 24, v5
	s_mul_i32 s10, s10, s16
	s_ashr_i32 s13, s14, 8
	s_lshl_b64 s[6:7], s[2:3], 8
	s_lshl_b32 s30, s12, 10
	v_or3_b32 v3, v3, v4, v5
	v_lshlrev_b32_e32 v4, 5, v14
	v_ashrrev_i16_sdwa v0, v6, sext(v0) dst_sel:DWORD dst_unused:UNUSED_PAD src0_sel:DWORD src1_sel:BYTE_0
	s_add_i32 s15, s15, s10
	s_mul_i32 s10, s8, s16
	v_and_b32_e32 v15, 32, v4
	v_bfe_i32 v16, v0, 0, 16
	s_add_u32 s36, s18, s10
	v_mul_lo_u32 v3, v3, s2
	v_add_u32_e32 v0, v15, v16
	s_addc_u32 s37, s29, s15
	s_add_i32 s31, s30, 16
	v_add_lshl_u32 v176, v3, v0, 1
	s_add_i32 m0, s31, 0x10000
	v_mov_b32_e32 v129, v177
	global_load_lds_dwordx4 v176, s[36:37]
	s_add_i32 m0, s31, 0x12000
	s_add_u32 s10, s36, s6
	global_load_lds_dwordx4 v128, s[36:37]
	s_addc_u32 s11, s37, s7
	s_add_i32 m0, s31, 0x14000
	v_lshl_add_u64 v[4:5], s[10:11], 0, v[176:177]
	global_load_lds_dwordx4 v176, s[10:11]
	s_add_i32 m0, s31, 0x16000
	v_lshl_add_u64 v[6:7], s[10:11], 0, v[128:129]
	global_load_lds_dwordx4 v128, s[10:11]
	v_readlane_b32 s10, v254, 25
	v_add_lshl_u32 v132, v0, v1, 1
	s_mov_b32 m0, s31
	v_readlane_b32 s11, v254, 26
	s_add_i32 s40, s31, 0x2000
	s_add_i32 s41, s31, 0x4000
	s_add_i32 s44, s31, 0x6000
	s_cmp_eq_u32 s13, 1
	v_lshl_add_u64 v[0:1], s[36:37], 0, v[176:177]
	s_barrier
	global_load_lds_dwordx4 v132, s[10:11]
	s_mov_b32 m0, s40
	v_lshl_add_u64 v[2:3], s[36:37], 0, v[128:129]
	global_load_lds_dwordx4 v130, s[10:11]
	v_readlane_b32 s10, v254, 27
	s_mov_b32 m0, s41
	v_readlane_b32 s11, v254, 28
	s_nop 4
	global_load_lds_dwordx4 v132, s[10:11]
	s_mov_b32 m0, s44
	s_nop 0
	global_load_lds_dwordx4 v130, s[10:11]
	s_cselect_b64 s[10:11], -1, 0
	s_cmp_lg_u32 s13, 1
	s_cbranch_scc1 .LBB0_627
	s_barrier

; #define PG8_WAIT_V(n) asm volatile("s_waitcnt vmcnt(" #n ")" ::: "memory")
; template <class Epi, bool ALIGN_EPI = PG8_ALIGN>
; __device__ __forceinline__ void gemm_phase(LAS unsigned char* lds, const Gemm g, const StaticOrder& S, const Epi& E) {
;     int tid = threadIdx.x; asm volatile("" : "+v"(tid));
;     const int wid = __builtin_amdgcn_readfirstlane(tid >> 6), lane = tid & 63, wr = wid >> 2, wc = wid & 3, fr = lane & 15, fq = lane >> 4;
;     int K = g.K; asm volatile("" : "+s"(K)); const int nt = K / BK, lda = g.lda;
;     unsigned voffA[2], voffB[2];
; #pragma unroll
;     for (int i = 0; i < 2; ++i) { int R, C; stage_rc(tid * 16 + i * 8192, R, C); const int Rb = Epi::PERM ? ((R & ~31) + perm32(R & 31)) : R;
;         voffA[i] = (unsigned)(R * lda + C) * 2u; voffB[i] = (unsigned)(Rb * K + C) * 2u; }
;     const size_t kstep = (size_t)(BK * 2);
;     const size_t hstepA = (size_t)HALF * lda * 2, hstepB = (size_t)HALF * K * 2;
;     const size_t tstepA = 2 * hstepA, tstepB = 2 * hstepB;
;     const unsigned ldsw = (unsigned)wid * 1024u;
;     const int aoff = lds_byte(wr * 64 + fr, fq * 8), boff = lds_byte(wc * 32 + fr, fq * 8);
;     ...
;     Unit cur, nxt; int ui = 0;
;     if (!S.next(0, cur)) return;
;     f32x4 acc[2][2][4][2];
; #pragma unroll
;     for (int a = 0; a < 2; ++a)
; #pragma unroll
;         for (int b = 0; b < 2; ++b)
; #pragma unroll
;             for (int m = 0; m < 4; ++m)
; #pragma unroll
;                 for (int n = 0; n < 2; ++n) acc[a][b][m][n] = (f32x4){0.f, 0.f, 0.f, 0.f};
;     bf16x8 At[4][2], B0[2][2], B1[2][2];
;     const char* cA = (const char*)g.A + (size_t)cur.pm * tstepA; const char* cB = (const char*)g.Bt + (size_t)cur.pn * tstepB;
;     PG8_STAGE(PG8_SB(0, 0), cB, voffB); PG8_STAGE(PG8_SB(0, 1), cB + hstepB, voffB); PG8_STAGE(PG8_SA(0, 0), cA, voffA); PG8_STAGE(PG8_SA(0, 1), cA + hstepA, voffA);
;     if (wr == 1) PG8_BAR;
;     PG8_WAIT_V(2); PG8_BAR;
; template <int PHM, int MIXM>
; __global__ void __launch_bounds__(512, 2) mega(Args Aval) {
;     ...
;         for (int rp = 0; rp < ((PROBE_DUP & 256) ? 2 : 1); ++rp) if ((PHM & 256) && IN(pb + 7)) { pg8::Gemm g{(const bf16_t*)(ws + WS_MIX), (const bf16_t*)(wl + WL_WOUT), T, DM, DM, DM}; pg8::StaticOrder S; S.init(T, DM, G, bx);
;             pg8::EpiStore E{(bf16_t*)(ws + WS_PROJ), DM, nullptr, 0, 1.0f}; pg8::gemm_phase(ldsl, g, S, E); }
.LBB0_884:
	v_readlane_b32 s2, v252, 2
	v_readlane_b32 s3, v252, 3
	v_readlane_b32 s4, v252, 0
	v_readlane_b32 s5, v252, 1
	s_cmp_le_i32 s4, s18
	s_cselect_b64 s[2:3], -1, 0
	s_cmp_lt_i32 s18, s5
	s_cselect_b64 s[4:5], -1, 0
	s_and_b64 s[6:7], s[2:3], s[4:5]
	s_andn2_b64 vcc, exec, s[6:7]
	s_cbranch_vccnz .LBB0_908
	v_readlane_b32 s4, v255, 23
	v_mov_b32_e32 v0, v238
	v_readlane_b32 s5, v255, 24
	s_movk_i32 s2, 0x800
	v_readfirstlane_b32 s16, v0
	s_and_b64 vcc, exec, s[4:5]
	s_cbranch_vccnz .LBB0_908
	v_lshlrev_b32_e32 v4, 4, v0
	v_add_u32_e32 v2, 0x2000, v4
	v_ashrrev_i32_e32 v1, 31, v2
	v_lshrrev_b32_e32 v1, 22, v1
	v_add_u32_e32 v1, v2, v1
	v_ashrrev_i32_e32 v1, 10, v1
	v_mul_i32_i24_e32 v3, 0x400, v1
	v_sub_u32_e32 v2, v2, v3
	v_lshrrev_b32_e32 v3, 4, v2
	v_bitop3_b32 v3, v3, v2, 32 bitop3:0x6c
	v_ashrrev_i32_e32 v2, 31, v3
	v_lshrrev_b32_e32 v2, 26, v2
	s_ashr_i32 s14, s16, 6
	s_ashr_i32 s3, s2, 31
	v_add_u32_e32 v5, v3, v2
	v_lshlrev_b32_e32 v6, 3, v1
	s_ashr_i32 s15, s16, 8
	s_lshl_b64 s[8:9], s[2:3], 8
	s_lshl_b64 s[10:11], s[2:3], 9
	s_lshl_b32 s18, s14, 10
	v_readlane_b32 s4, v255, 17
	v_ashrrev_i32_e32 v2, 6, v5
	v_and_b32_e32 v6, -16, v6
	s_add_u32 s26, s4, 0x5300000
	v_readlane_b32 s4, v255, 18
	v_add_u32_e32 v6, v2, v6
	s_addc_u32 s27, s4, 0
	v_and_b32_e32 v7, 3, v2
	s_mov_b32 s4, 0x7fffffe0
	v_lshrrev_b32_e32 v8, 2, v6
	v_lshlrev_b32_e32 v9, 1, v6
	v_and_b32_e32 v5, 0xc0, v5
	v_and_or_b32 v7, v6, s4, v7
	v_and_b32_e32 v8, 4, v8
	v_and_b32_e32 v9, 24, v9
	v_sub_u32_e32 v3, v3, v5
	v_mov_b32_e32 v12, 1
	v_or3_b32 v7, v7, v8, v9
	v_lshlrev_b32_e32 v8, 5, v1
	v_ashrrev_i16_sdwa v3, v12, sext(v3) dst_sel:DWORD dst_unused:UNUSED_PAD src0_sel:DWORD src1_sel:BYTE_0
	v_and_b32_e32 v8, 32, v8
	v_bfe_i32 v3, v3, 0, 16
	v_mul_lo_u32 v7, v7, s2
	v_add_u32_e32 v5, v8, v3
	v_lshlrev_b32_e32 v6, 12, v6
	v_add_lshl_u32 v128, v7, v5, 1
	v_lshl_add_u32 v130, v5, 1, v6
	v_bfe_i32 v5, v0, 27, 1
	v_lshrrev_b32_e32 v5, 22, v5
	v_add_u32_e32 v5, v4, v5
	v_and_b32_e32 v5, 0xfffffc00, v5
	v_sub_u32_e32 v4, v4, v5
	v_lshrrev_b32_e32 v5, 4, v4
	v_bitop3_b32 v6, v5, v4, 32 bitop3:0x6c
	v_ashrrev_i32_e32 v5, 31, v0
	v_lshrrev_b32_e32 v5, 26, v5
	v_ashrrev_i32_e32 v4, 31, v6
	v_add_u32_e32 v5, v0, v5
	v_lshrrev_b32_e32 v4, 26, v4
	v_ashrrev_i32_e32 v5, 6, v5
	v_add_u32_e32 v7, v6, v4
	v_lshlrev_b32_e32 v8, 3, v5
	v_ashrrev_i32_e32 v4, 6, v7
	v_and_b32_e32 v8, -16, v8
	v_readlane_b32 s20, v253, 61
	v_add_u32_e32 v8, v4, v8
	v_and_b32_e32 v9, 3, v4
	v_readlane_b32 s21, v253, 62
	v_and_or_b32 v9, v8, s4, v9
	s_mul_i32 s4, s10, s21
	s_mul_hi_u32 s5, s10, s20
	v_lshrrev_b32_e32 v10, 2, v8
	v_lshlrev_b32_e32 v11, 1, v8
	v_and_b32_e32 v7, 0xc0, v7
	s_add_i32 s12, s5, s4
	s_lshr_b64 s[4:5], s[2:3], 23
	v_and_b32_e32 v10, 4, v10
	v_and_b32_e32 v11, 24, v11
	v_sub_u32_e32 v6, v6, v7
	s_mul_i32 s4, s4, s20
	v_or3_b32 v9, v9, v10, v11
	v_lshlrev_b32_e32 v10, 5, v5
	v_ashrrev_i16_sdwa v6, v12, sext(v6) dst_sel:DWORD dst_unused:UNUSED_PAD src0_sel:DWORD src1_sel:BYTE_0
	s_add_i32 s12, s12, s4
	s_mul_i32 s4, s10, s20
	v_and_b32_e32 v10, 32, v10
	v_bfe_i32 v6, v6, 0, 16
	s_add_u32 s40, s26, s4
	v_mul_lo_u32 v9, v9, s2
	v_add_u32_e32 v7, v10, v6
	s_addc_u32 s41, s27, s12
	s_add_i32 s29, s18, 16
	v_add_lshl_u32 v176, v9, v7, 1
	s_add_i32 m0, s29, 0x10000
	v_lshlrev_b32_e32 v8, 12, v8
	global_load_lds_dwordx4 v176, s[40:41]
	s_add_i32 m0, s29, 0x12000
	s_add_u32 s4, s40, s8
	global_load_lds_dwordx4 v128, s[40:41]
	s_addc_u32 s5, s41, s9
	s_add_i32 m0, s29, 0x14000
	v_readlane_b32 s12, v254, 41
	global_load_lds_dwordx4 v176, s[4:5]
	s_add_i32 m0, s29, 0x16000
	v_lshl_add_u32 v132, v7, 1, v8
	global_load_lds_dwordx4 v128, s[4:5]
	s_mov_b32 m0, s29
	v_readlane_b32 s13, v254, 42
	s_add_i32 s30, s29, 0x2000
	s_add_i32 s31, s29, 0x4000
	s_add_i32 s44, s29, 0x6000
	s_cmp_eq_u32 s15, 1
	s_nop 0
	s_barrier
	global_load_lds_dwordx4 v132, s[12:13]
	s_mov_b32 m0, s30
	s_nop 0
	global_load_lds_dwordx4 v130, s[12:13]
	v_readlane_b32 s12, v254, 43
	s_mov_b32 m0, s31
	v_readlane_b32 s13, v254, 44
	s_nop 4
	global_load_lds_dwordx4 v132, s[12:13]
	s_mov_b32 m0, s44
	s_nop 0
	global_load_lds_dwordx4 v130, s[12:13]
	s_cselect_b64 s[12:13], -1, 0
	s_cmp_lg_u32 s15, 1
	s_cbranch_scc1 .LBB0_888
	s_barrier

; template <class Epi, bool ALIGN_EPI = PG8_ALIGN>
; __device__ __forceinline__ void gemm_phase(LAS unsigned char* lds, const Gemm g, const StaticOrder& S, const Epi& E) {
;     int tid = threadIdx.x; asm volatile("" : "+v"(tid));
;     const int wid = __builtin_amdgcn_readfirstlane(tid >> 6), lane = tid & 63, wr = wid >> 2, wc = wid & 3, fr = lane & 15, fq = lane >> 4;
;     int K = g.K; asm volatile("" : "+s"(K)); const int nt = K / BK, lda = g.lda;
;     unsigned voffA[2], voffB[2];
; #pragma unroll
;     for (int i = 0; i < 2; ++i) { int R, C; stage_rc(tid * 16 + i * 8192, R, C); const int Rb = Epi::PERM ? ((R & ~31) + perm32(R & 31)) : R;
;         voffA[i] = (unsigned)(R * lda + C) * 2u; voffB[i] = (unsigned)(Rb * K + C) * 2u; }
;     const size_t kstep = (size_t)(BK * 2);
;     const size_t hstepA = (size_t)HALF * lda * 2, hstepB = (size_t)HALF * K * 2;
;     const size_t tstepA = 2 * hstepA, tstepB = 2 * hstepB;
;     const unsigned ldsw = (unsigned)wid * 1024u;
;     const int aoff = lds_byte(wr * 64 + fr, fq * 8), boff = lds_byte(wc * 32 + fr, fq * 8);
;     ...
;     Unit cur, nxt; int ui = 0;
;     if (!S.next(0, cur)) return;
;     f32x4 acc[2][2][4][2];
; #pragma unroll
;     for (int a = 0; a < 2; ++a)
; #pragma unroll
;         for (int b = 0; b < 2; ++b)
; #pragma unroll
;             for (int m = 0; m < 4; ++m)
; #pragma unroll
;                 for (int n = 0; n < 2; ++n) acc[a][b][m][n] = (f32x4){0.f, 0.f, 0.f, 0.f};
;     bf16x8 At[4][2], B0[2][2], B1[2][2];
;     const char* cA = (const char*)g.A + (size_t)cur.pm * tstepA; const char* cB = (const char*)g.Bt + (size_t)cur.pn * tstepB;
;     PG8_STAGE(PG8_SB(0, 0), cB, voffB); PG8_STAGE(PG8_SB(0, 1), cB + hstepB, voffB); PG8_STAGE(PG8_SA(0, 0), cA, voffA); PG8_STAGE(PG8_SA(0, 1), cA + hstepA, voffA);
;     if (wr == 1) PG8_BAR;
;     PG8_WAIT_V(2); PG8_BAR;
;     PG8_STAGE(PG8_SB(1, 0), cB + kstep, voffB); PG8_STAGE(PG8_SA(1, 0), cA + kstep, voffA); PG8_STAGE(PG8_SB(1, 1), cB + hstepB + kstep, voffB);
; template <int PHM, int MIXM>
; __global__ void __launch_bounds__(512, 2) mega(Args Aval) {
;     ...
;         if ((PHM & 1024) && IN(pb + 9)) { pg8::Gemm g{XB, (const bf16_t*)(wl + WL_W2T), T, 2 * DFF + DM, DM, DM}; pg8::StaticOrder S; S.init(T, 2 * DFF + DM, G, bx);
;             pg8::EpiSwiGLU E{(bf16_t*)(ws + WS_ACT), (bf16_t*)(ws + WS_PP), A->in[36] + l * DM, 44}; pg8::gemm_phase(ldsl, g, S, E); }
.LBB0_1015:
	s_andn2_b64 vcc, exec, s[2:3]
	s_cbranch_vccnz .LBB0_1089
	v_readlane_b32 s6, v253, 49
	v_mov_b32_e32 v8, v238
	v_readlane_b32 s7, v253, 50
	s_movk_i32 s2, 0x800
	v_readfirstlane_b32 s14, v8
	s_andn2_b64 vcc, exec, s[6:7]
	s_cbranch_vccnz .LBB0_1039
	v_lshlrev_b32_e32 v0, 4, v8
	v_add_u32_e32 v1, 0x2000, v0
	v_ashrrev_i32_e32 v2, 31, v1
	v_lshrrev_b32_e32 v2, 22, v2
	v_add_u32_e32 v2, v1, v2
	v_ashrrev_i32_e32 v9, 10, v2
	v_mul_i32_i24_e32 v2, 0x400, v9
	v_sub_u32_e32 v1, v1, v2
	v_lshrrev_b32_e32 v2, 4, v1
	v_bitop3_b32 v1, v2, v1, 32 bitop3:0x6c
	v_ashrrev_i32_e32 v2, 31, v1
	v_lshrrev_b32_e32 v2, 26, v2
	v_add_u32_e32 v2, v1, v2
	v_lshlrev_b32_e32 v3, 3, v9
	v_ashrrev_i32_e32 v10, 6, v2
	v_and_b32_e32 v3, -16, v3
	v_add_u32_e32 v3, v10, v3
	v_and_b32_e32 v4, 3, v10
	s_mov_b32 s8, 0x7fffffe0
	v_lshrrev_b32_e32 v5, 2, v3
	v_lshlrev_b32_e32 v6, 1, v3
	v_and_or_b32 v4, v3, s8, v4
	v_and_b32_e32 v5, 4, v5
	v_and_b32_e32 v6, 24, v6
	v_and_b32_e32 v2, 0xc0, v2
	v_or3_b32 v4, v4, v5, v6
	v_sub_u32_e32 v1, v1, v2
	v_mov_b32_e32 v6, 1
	v_lshlrev_b32_e32 v5, 5, v9
	v_ashrrev_i16_sdwa v1, v6, sext(v1) dst_sel:DWORD dst_unused:UNUSED_PAD src0_sel:DWORD src1_sel:BYTE_0
	v_and_b32_e32 v5, 32, v5
	v_bfe_i32 v11, v1, 0, 16
	v_mul_lo_u32 v4, v4, s2
	v_add_u32_e32 v1, v5, v11
	v_lshlrev_b32_e32 v2, 12, v3
	v_add_lshl_u32 v184, v4, v1, 1
	v_lshl_add_u32 v186, v1, 1, v2
	v_bfe_i32 v1, v8, 27, 1
	v_lshrrev_b32_e32 v1, 22, v1
	v_add_u32_e32 v1, v0, v1
	v_and_b32_e32 v1, 0xfffffc00, v1
	v_sub_u32_e32 v0, v0, v1
	v_lshrrev_b32_e32 v1, 4, v0
	v_ashrrev_i32_e32 v2, 31, v8
	v_bitop3_b32 v0, v1, v0, 32 bitop3:0x6c
	v_lshrrev_b32_e32 v2, 26, v2
	v_ashrrev_i32_e32 v1, 31, v0
	v_add_u32_e32 v2, v8, v2
	v_readlane_b32 s3, v255, 17
	v_lshrrev_b32_e32 v1, 26, v1
	v_ashrrev_i32_e32 v13, 6, v2
	s_add_u32 s44, s3, 0x5b00000
	v_readlane_b32 s3, v255, 18
	v_add_u32_e32 v1, v0, v1
	v_lshlrev_b32_e32 v2, 3, v13
	s_addc_u32 s45, s3, 0
	s_ashr_i32 s3, s2, 31
	v_ashrrev_i32_e32 v12, 6, v1
	v_and_b32_e32 v2, -16, v2
	v_readlane_b32 s16, v254, 46
	s_lshl_b64 s[6:7], s[2:3], 9
	v_add_u32_e32 v2, v12, v2
	v_and_b32_e32 v3, 3, v12
	v_readlane_b32 s17, v254, 47
	v_and_or_b32 v3, v2, s8, v3
	s_mul_i32 s8, s6, s17
	s_mul_hi_u32 s9, s6, s16
	v_lshrrev_b32_e32 v4, 2, v2
	v_lshlrev_b32_e32 v5, 1, v2
	v_and_b32_e32 v1, 0xc0, v1
	s_add_i32 s15, s9, s8
	s_lshr_b64 s[8:9], s[2:3], 23
	s_ashr_i32 s12, s14, 6
	v_and_b32_e32 v4, 4, v4
	v_and_b32_e32 v5, 24, v5
	v_sub_u32_e32 v0, v0, v1
	s_mul_i32 s8, s8, s16
	s_load_dwordx2 s[10:11], s[4:5], 0x120
	s_ashr_i32 s13, s14, 8
	s_lshl_b64 s[4:5], s[2:3], 8
	s_lshl_b32 s46, s12, 10
	v_or3_b32 v3, v3, v4, v5
	v_lshlrev_b32_e32 v4, 5, v13
	v_ashrrev_i16_sdwa v0, v6, sext(v0) dst_sel:DWORD dst_unused:UNUSED_PAD src0_sel:DWORD src1_sel:BYTE_0
	s_add_i32 s15, s15, s8
	s_mul_i32 s8, s6, s16
	v_and_b32_e32 v4, 32, v4
	v_bfe_i32 v14, v0, 0, 16
	s_add_u32 s24, s44, s8
	v_mul_lo_u32 v3, v3, s2
	v_add_u32_e32 v0, v4, v14
	s_addc_u32 s25, s45, s15
	s_add_i32 s47, s46, 16
	v_add_lshl_u32 v188, v3, v0, 1
	s_add_i32 m0, s47, 0x10000
	v_mov_b32_e32 v189, v177
	global_load_lds_dwordx4 v188, s[24:25]
	s_add_i32 m0, s47, 0x12000
	s_add_u32 s8, s24, s4
	global_load_lds_dwordx4 v184, s[24:25]
	s_addc_u32 s9, s25, s5
	s_add_i32 m0, s47, 0x14000
	v_mov_b32_e32 v185, v177
	global_load_lds_dwordx4 v188, s[8:9]
	s_add_i32 m0, s47, 0x16000
	v_lshlrev_b32_e32 v1, 12, v2
	v_lshl_add_u64 v[4:5], s[8:9], 0, v[188:189]
	v_lshl_add_u64 v[6:7], s[8:9], 0, v[184:185]
	global_load_lds_dwordx4 v184, s[8:9]
	v_readlane_b32 s8, v254, 51
	v_lshl_add_u32 v190, v0, 1, v1
	s_mov_b32 m0, s47
	v_readlane_b32 s9, v254, 52
	s_add_i32 s48, s47, 0x2000
	s_add_i32 s49, s47, 0x4000
	s_add_i32 s50, s47, 0x6000
	s_cmp_eq_u32 s13, 1
	v_lshl_add_u64 v[0:1], s[24:25], 0, v[188:189]
	s_barrier
	global_load_lds_dwordx4 v190, s[8:9]
	s_mov_b32 m0, s48
	v_lshl_add_u64 v[2:3], s[24:25], 0, v[184:185]
	global_load_lds_dwordx4 v186, s[8:9]
	v_readlane_b32 s8, v254, 53
	s_mov_b32 m0, s49
	v_readlane_b32 s9, v254, 54
	s_nop 4
	global_load_lds_dwordx4 v190, s[8:9]
	s_mov_b32 m0, s50
	s_nop 0
	global_load_lds_dwordx4 v186, s[8:9]
	s_cselect_b64 s[8:9], -1, 0
	s_cmp_lg_u32 s13, 1
	s_cbranch_scc1 .LBB0_1019
	s_barrier

; #define PG8_WAIT_V(n) asm volatile("s_waitcnt vmcnt(" #n ")" ::: "memory")
; template <class Epi, bool ALIGN_EPI = PG8_ALIGN>
; __device__ __forceinline__ void gemm_phase(LAS unsigned char* lds, const Gemm g, const StaticOrder& S, const Epi& E) {
;     int tid = threadIdx.x; asm volatile("" : "+v"(tid));
;     const int wid = __builtin_amdgcn_readfirstlane(tid >> 6), lane = tid & 63, wr = wid >> 2, wc = wid & 3, fr = lane & 15, fq = lane >> 4;
;     int K = g.K; asm volatile("" : "+s"(K)); const int nt = K / BK, lda = g.lda;
;     unsigned voffA[2], voffB[2];
; #pragma unroll
;     for (int i = 0; i < 2; ++i) { int R, C; stage_rc(tid * 16 + i * 8192, R, C); const int Rb = Epi::PERM ? ((R & ~31) + perm32(R & 31)) : R;
;         voffA[i] = (unsigned)(R * lda + C) * 2u; voffB[i] = (unsigned)(Rb * K + C) * 2u; }
;     const size_t kstep = (size_t)(BK * 2);
;     const size_t hstepA = (size_t)HALF * lda * 2, hstepB = (size_t)HALF * K * 2;
;     const size_t tstepA = 2 * hstepA, tstepB = 2 * hstepB;
;     const unsigned ldsw = (unsigned)wid * 1024u;
;     const int aoff = lds_byte(wr * 64 + fr, fq * 8), boff = lds_byte(wc * 32 + fr, fq * 8);
;     ...
;     Unit cur, nxt; int ui = 0;
;     if (!S.next(0, cur)) return;
;     f32x4 acc[2][2][4][2];
; #pragma unroll
;     for (int a = 0; a < 2; ++a)
; #pragma unroll
;         for (int b = 0; b < 2; ++b)
; #pragma unroll
;             for (int m = 0; m < 4; ++m)
; #pragma unroll
;                 for (int n = 0; n < 2; ++n) acc[a][b][m][n] = (f32x4){0.f, 0.f, 0.f, 0.f};
;     bf16x8 At[4][2], B0[2][2], B1[2][2];
;     const char* cA = (const char*)g.A + (size_t)cur.pm * tstepA; const char* cB = (const char*)g.Bt + (size_t)cur.pn * tstepB;
;     PG8_STAGE(PG8_SB(0, 0), cB, voffB); PG8_STAGE(PG8_SB(0, 1), cB + hstepB, voffB); PG8_STAGE(PG8_SA(0, 0), cA, voffA); PG8_STAGE(PG8_SA(0, 1), cA + hstepA, voffA);
;     if (wr == 1) PG8_BAR;
;     PG8_WAIT_V(2); PG8_BAR;
; template <int PHM, int MIXM>
; __global__ void __launch_bounds__(512, 2) mega(Args Aval) {
;     ...
;         for (int rp = 0; rp < ((PROBE_DUP & 256) ? 2 : 1); ++rp) if ((PHM & 2048) && IN(pb + 10)) { pg8::Gemm g{(const bf16_t*)(ws + WS_ACT), (const bf16_t*)(wl + WL_W2D), T, DM, DFF, DFF}; pg8::StaticOrder S; S.init(T, DM, G, bx);
;             pg8::EpiStore E{(bf16_t*)(ws + WS_MIX), DM, nullptr, 0, 0.5f}; pg8::gemm_phase(ldsl, g, S, E); }
.LBB0_1089:
	v_readlane_b32 s2, v252, 2
	v_readlane_b32 s3, v252, 3
	v_readlane_b32 s4, v252, 0
	v_readlane_b32 s5, v252, 1
	s_cmp_le_i32 s4, s18
	s_cselect_b64 s[2:3], -1, 0
	s_cmp_lt_i32 s18, s5
	s_cselect_b64 s[4:5], -1, 0
	s_and_b64 s[4:5], s[2:3], s[4:5]
	s_andn2_b64 vcc, exec, s[4:5]
	s_cbranch_vccnz .LBB0_1116
	v_readlane_b32 s6, v255, 23
	v_mov_b32_e32 v8, v238
	v_readlane_b32 s7, v255, 24
	s_movk_i32 s2, 0x1600
	v_readfirstlane_b32 s14, v8
	s_and_b64 vcc, exec, s[6:7]
	s_cbranch_vccnz .LBB0_1116
	v_lshlrev_b32_e32 v0, 4, v8
	v_add_u32_e32 v1, 0x2000, v0
	v_ashrrev_i32_e32 v2, 31, v1
	v_lshrrev_b32_e32 v2, 22, v2
	v_add_u32_e32 v2, v1, v2
	v_ashrrev_i32_e32 v9, 10, v2
	v_mul_i32_i24_e32 v2, 0x400, v9
	v_sub_u32_e32 v1, v1, v2
	v_lshrrev_b32_e32 v2, 4, v1
	v_bitop3_b32 v1, v2, v1, 32 bitop3:0x6c
	v_ashrrev_i32_e32 v2, 31, v1
	v_lshrrev_b32_e32 v2, 26, v2
	s_ashr_i32 s12, s14, 6
	s_ashr_i32 s3, s2, 31
	v_add_u32_e32 v2, v1, v2
	v_lshlrev_b32_e32 v3, 3, v9
	s_ashr_i32 s13, s14, 8
	s_lshl_b64 s[6:7], s[2:3], 8
	s_lshl_b64 s[8:9], s[2:3], 9
	s_lshl_b32 s18, s12, 10
	v_readlane_b32 s10, v255, 17
	v_ashrrev_i32_e32 v10, 6, v2
	v_and_b32_e32 v3, -16, v3
	s_add_u32 s29, s10, 0x8f00000
	v_readlane_b32 s10, v255, 18
	v_add_u32_e32 v3, v10, v3
	s_addc_u32 s30, s10, 0
	v_and_b32_e32 v4, 3, v10
	s_mov_b32 s10, 0x7fffffe0
	v_lshrrev_b32_e32 v5, 2, v3
	v_lshlrev_b32_e32 v6, 1, v3
	v_and_or_b32 v4, v3, s10, v4
	v_and_b32_e32 v5, 4, v5
	v_and_b32_e32 v6, 24, v6
	v_and_b32_e32 v2, 0xc0, v2
	v_or3_b32 v4, v4, v5, v6
	v_sub_u32_e32 v1, v1, v2
	v_mov_b32_e32 v6, 1
	v_lshlrev_b32_e32 v5, 5, v9
	v_ashrrev_i16_sdwa v1, v6, sext(v1) dst_sel:DWORD dst_unused:UNUSED_PAD src0_sel:DWORD src1_sel:BYTE_0
	v_and_b32_e32 v11, 32, v5
	v_bfe_i32 v12, v1, 0, 16
	s_movk_i32 s11, 0x1600
	v_mul_lo_u32 v4, v4, s2
	v_add_u32_e32 v1, v11, v12
	v_mul_lo_u32 v2, v3, s11
	v_add_lshl_u32 v128, v4, v1, 1
	v_add_lshl_u32 v130, v1, v2, 1
	v_bfe_i32 v1, v8, 27, 1
	v_lshrrev_b32_e32 v1, 22, v1
	v_add_u32_e32 v1, v0, v1
	v_and_b32_e32 v1, 0xfffffc00, v1
	v_sub_u32_e32 v0, v0, v1
	v_lshrrev_b32_e32 v1, 4, v0
	v_ashrrev_i32_e32 v2, 31, v8
	v_bitop3_b32 v0, v1, v0, 32 bitop3:0x6c
	v_lshrrev_b32_e32 v2, 26, v2
	v_ashrrev_i32_e32 v1, 31, v0
	v_add_u32_e32 v2, v8, v2
	v_lshrrev_b32_e32 v1, 26, v1
	v_ashrrev_i32_e32 v14, 6, v2
	v_add_u32_e32 v1, v0, v1
	v_lshlrev_b32_e32 v2, 3, v14
	v_ashrrev_i32_e32 v13, 6, v1
	v_and_b32_e32 v2, -16, v2
	v_readlane_b32 s16, v253, 61
	v_add_u32_e32 v2, v13, v2
	v_and_b32_e32 v3, 3, v13
	v_and_b32_e32 v1, 0xc0, v1
	v_readlane_b32 s17, v253, 62
	v_and_or_b32 v3, v2, s10, v3
	v_sub_u32_e32 v0, v0, v1
	v_mul_lo_u32 v1, v2, s11
	s_mul_i32 s10, s8, s17
	s_mul_hi_u32 s11, s8, s16
	v_lshrrev_b32_e32 v4, 2, v2
	v_lshlrev_b32_e32 v5, 1, v2
	s_add_i32 s15, s11, s10
	s_lshr_b64 s[10:11], s[2:3], 23
	v_and_b32_e32 v4, 4, v4
	v_and_b32_e32 v5, 24, v5
	s_mul_i32 s10, s10, s16
	v_or3_b32 v3, v3, v4, v5
	v_lshlrev_b32_e32 v4, 5, v14
	v_ashrrev_i16_sdwa v0, v6, sext(v0) dst_sel:DWORD dst_unused:UNUSED_PAD src0_sel:DWORD src1_sel:BYTE_0
	s_add_i32 s15, s15, s10
	s_mul_i32 s10, s8, s16
	v_and_b32_e32 v15, 32, v4
	v_bfe_i32 v16, v0, 0, 16
	s_add_u32 s36, s29, s10
	v_mul_lo_u32 v3, v3, s2
	v_add_u32_e32 v0, v15, v16
	s_addc_u32 s37, s30, s15
	s_add_i32 s31, s18, 16
	v_add_lshl_u32 v176, v3, v0, 1
	s_add_i32 m0, s31, 0x10000
	v_mov_b32_e32 v129, v177
	global_load_lds_dwordx4 v176, s[36:37]
	s_add_i32 m0, s31, 0x12000
	s_add_u32 s10, s36, s6
	global_load_lds_dwordx4 v128, s[36:37]
	s_addc_u32 s11, s37, s7
	s_add_i32 m0, s31, 0x14000
	v_lshl_add_u64 v[4:5], s[10:11], 0, v[176:177]
	global_load_lds_dwordx4 v176, s[10:11]
	s_add_i32 m0, s31, 0x16000
	v_lshl_add_u64 v[6:7], s[10:11], 0, v[128:129]
	global_load_lds_dwordx4 v128, s[10:11]
	v_readlane_b32 s10, v253, 63
	v_add_lshl_u32 v132, v0, v1, 1
	s_mov_b32 m0, s31
	v_readlane_b32 s11, v254, 0
	s_add_i32 s42, s31, 0x2000
	s_add_i32 s43, s31, 0x4000
	s_add_i32 s44, s31, 0x6000
	s_cmp_eq_u32 s13, 1
	v_lshl_add_u64 v[0:1], s[36:37], 0, v[176:177]
	s_barrier
	global_load_lds_dwordx4 v132, s[10:11]
	s_mov_b32 m0, s42
	v_lshl_add_u64 v[2:3], s[36:37], 0, v[128:129]
	global_load_lds_dwordx4 v130, s[10:11]
	v_readlane_b32 s10, v254, 1
	s_mov_b32 m0, s43
	v_readlane_b32 s11, v254, 2
	s_nop 4
	global_load_lds_dwordx4 v132, s[10:11]
	s_mov_b32 m0, s44
	s_nop 0
	global_load_lds_dwordx4 v130, s[10:11]
	s_cselect_b64 s[10:11], -1, 0
	s_cmp_lg_u32 s13, 1
	s_cbranch_scc1 .LBB0_1093
	s_barrier
